# v7 + s_waitcnt vmcnt(0) before each K-loop entry (drain epilogue stores before the counted waits)
# speedup vs baseline: 1.0018x; 1.0018x over previous
.LBB0_108:
	s_ashr_i32 s15, s14, 31
	s_lshl_b64 s[16:17], s[14:15], 21
	v_readlane_b32 s18, v251, 17
	v_readlane_b32 s19, v251, 18
	s_add_u32 s16, s18, s16
	s_addc_u32 s17, s19, s17
	s_and_b64 s[18:19], s[2:3], exec
	s_cselect_b32 s15, s17, s21
	s_cselect_b32 s42, s16, s20
	s_ashr_i32 s13, s12, 31
	s_lshl_b64 s[18:19], s[12:13], 21
	s_add_u32 s18, s76, s18
	s_addc_u32 s19, s77, s19
	s_and_b64 s[24:25], s[2:3], exec
	s_cselect_b32 s13, s19, s23
	s_cselect_b32 s43, s18, s22
	s_add_u32 s20, s20, 0x104000
	s_addc_u32 s21, s21, 0
	s_add_u32 s44, s22, 0x8000
	v_mov_b32_e32 v66, 0
	s_addc_u32 s45, s23, 0
	s_mov_b32 s46, -2
	v_mov_b32_e32 v67, v66
	v_mov_b32_e32 v68, v66
	v_mov_b32_e32 v69, v66
	v_mov_b32_e32 v70, v66
	v_mov_b32_e32 v71, v66
	v_mov_b32_e32 v72, v66
	v_mov_b32_e32 v73, v66
	v_mov_b32_e32 v74, v66
	v_mov_b32_e32 v75, v66
	v_mov_b32_e32 v76, v66
	v_mov_b32_e32 v77, v66
	v_mov_b32_e32 v78, v66
	v_mov_b32_e32 v79, v66
	v_mov_b32_e32 v80, v66
	v_mov_b32_e32 v81, v66
	v_mov_b32_e32 v82, v66
	v_mov_b32_e32 v83, v66
	v_mov_b32_e32 v84, v66
	v_mov_b32_e32 v85, v66
	v_mov_b32_e32 v86, v66
	v_mov_b32_e32 v87, v66
	v_mov_b32_e32 v88, v66
	v_mov_b32_e32 v89, v66
	v_mov_b32_e32 v90, v66
	v_mov_b32_e32 v91, v66
	v_mov_b32_e32 v92, v66
	v_mov_b32_e32 v93, v66
	v_mov_b32_e32 v94, v66
	v_mov_b32_e32 v95, v66
	v_mov_b32_e32 v96, v66
	v_mov_b32_e32 v97, v66
	v_mov_b32_e32 v2, v66
	v_mov_b32_e32 v3, v66
	v_mov_b32_e32 v4, v66
	v_mov_b32_e32 v5, v66
	v_mov_b32_e32 v6, v66
	v_mov_b32_e32 v7, v66
	v_mov_b32_e32 v8, v66
	v_mov_b32_e32 v9, v66
	v_mov_b32_e32 v10, v66
	v_mov_b32_e32 v11, v66
	v_mov_b32_e32 v12, v66
	v_mov_b32_e32 v13, v66
	v_mov_b32_e32 v14, v66
	v_mov_b32_e32 v15, v66
	v_mov_b32_e32 v16, v66
	v_mov_b32_e32 v17, v66
	v_mov_b32_e32 v18, v66
	v_mov_b32_e32 v19, v66
	v_mov_b32_e32 v20, v66
	v_mov_b32_e32 v21, v66
	v_mov_b32_e32 v22, v66
	v_mov_b32_e32 v23, v66
	v_mov_b32_e32 v24, v66
	v_mov_b32_e32 v25, v66
	v_mov_b32_e32 v26, v66
	v_mov_b32_e32 v27, v66
	v_mov_b32_e32 v28, v66
	v_mov_b32_e32 v29, v66
	v_mov_b32_e32 v30, v66
	v_mov_b32_e32 v31, v66
	v_mov_b32_e32 v32, v66
	v_mov_b32_e32 v33, v66
	v_mov_b32_e32 v98, v66
	v_mov_b32_e32 v99, v66
	v_mov_b32_e32 v100, v66
	v_mov_b32_e32 v101, v66
	v_mov_b32_e32 v102, v66
	v_mov_b32_e32 v103, v66
	v_mov_b32_e32 v104, v66
	v_mov_b32_e32 v105, v66
	v_mov_b32_e32 v106, v66
	v_mov_b32_e32 v107, v66
	v_mov_b32_e32 v108, v66
	v_mov_b32_e32 v109, v66
	v_mov_b32_e32 v110, v66
	v_mov_b32_e32 v111, v66
	v_mov_b32_e32 v112, v66
	v_mov_b32_e32 v113, v66
	v_mov_b32_e32 v114, v66
	v_mov_b32_e32 v115, v66
	v_mov_b32_e32 v116, v66
	v_mov_b32_e32 v117, v66
	v_mov_b32_e32 v118, v66
	v_mov_b32_e32 v119, v66
	v_mov_b32_e32 v120, v66
	v_mov_b32_e32 v121, v66
	v_mov_b32_e32 v122, v66
	v_mov_b32_e32 v123, v66
	v_mov_b32_e32 v124, v66
	v_mov_b32_e32 v125, v66
	v_mov_b32_e32 v126, v66
	v_mov_b32_e32 v127, v66
	v_mov_b32_e32 v128, v66
	v_mov_b32_e32 v129, v66
	v_mov_b32_e32 v34, v66
	v_mov_b32_e32 v35, v66
	v_mov_b32_e32 v36, v66
	v_mov_b32_e32 v37, v66
	v_mov_b32_e32 v38, v66
	v_mov_b32_e32 v39, v66
	v_mov_b32_e32 v40, v66
	v_mov_b32_e32 v41, v66
	v_mov_b32_e32 v42, v66
	v_mov_b32_e32 v43, v66
	v_mov_b32_e32 v44, v66
	v_mov_b32_e32 v45, v66
	v_mov_b32_e32 v46, v66
	v_mov_b32_e32 v47, v66
	v_mov_b32_e32 v48, v66
	v_mov_b32_e32 v49, v66
	v_mov_b32_e32 v50, v66
	v_mov_b32_e32 v51, v66
	v_mov_b32_e32 v52, v66
	v_mov_b32_e32 v53, v66
	v_mov_b32_e32 v54, v66
	v_mov_b32_e32 v55, v66
	v_mov_b32_e32 v56, v66
	v_mov_b32_e32 v57, v66
	v_mov_b32_e32 v58, v66
	v_mov_b32_e32 v59, v66
	v_mov_b32_e32 v60, v66
	v_mov_b32_e32 v61, v66
	v_mov_b32_e32 v62, v66
	v_mov_b32_e32 v63, v66
	v_mov_b32_e32 v64, v66
	v_mov_b32_e32 v65, v66
	s_waitcnt vmcnt(0)

.LBB0_375:
	s_ashr_i32 s21, s20, 31
	s_lshl_b64 s[22:23], s[20:21], 21
	v_readlane_b32 s24, v251, 17
	v_readlane_b32 s25, v251, 18
	s_add_u32 s22, s24, s22
	s_addc_u32 s23, s25, s23
	s_and_b64 s[24:25], s[2:3], exec
	s_cselect_b32 s21, s23, s27
	s_cselect_b32 s80, s22, s26
	s_ashr_i32 s19, s18, 31
	s_lshl_b64 s[24:25], s[18:19], 21
	s_add_u32 s24, s42, s24
	s_addc_u32 s25, s43, s25
	s_and_b64 s[36:37], s[2:3], exec
	s_cselect_b32 s19, s25, s35
	s_cselect_b32 s81, s24, s34
	s_add_u32 s26, s26, 0x104000
	s_addc_u32 s27, s27, 0
	s_add_u32 s83, s34, 0x8000
	v_mov_b32_e32 v66, 0
	s_addc_u32 s86, s35, 0
	s_mov_b32 s87, -2
	v_mov_b32_e32 v67, v66
	v_mov_b32_e32 v68, v66
	v_mov_b32_e32 v69, v66
	v_mov_b32_e32 v70, v66
	v_mov_b32_e32 v71, v66
	v_mov_b32_e32 v72, v66
	v_mov_b32_e32 v73, v66
	v_mov_b32_e32 v74, v66
	v_mov_b32_e32 v75, v66
	v_mov_b32_e32 v76, v66
	v_mov_b32_e32 v77, v66
	v_mov_b32_e32 v78, v66
	v_mov_b32_e32 v79, v66
	v_mov_b32_e32 v80, v66
	v_mov_b32_e32 v81, v66
	v_mov_b32_e32 v82, v66
	v_mov_b32_e32 v83, v66
	v_mov_b32_e32 v84, v66
	v_mov_b32_e32 v85, v66
	v_mov_b32_e32 v86, v66
	v_mov_b32_e32 v87, v66
	v_mov_b32_e32 v88, v66
	v_mov_b32_e32 v89, v66
	v_mov_b32_e32 v90, v66
	v_mov_b32_e32 v91, v66
	v_mov_b32_e32 v92, v66
	v_mov_b32_e32 v93, v66
	v_mov_b32_e32 v94, v66
	v_mov_b32_e32 v95, v66
	v_mov_b32_e32 v96, v66
	v_mov_b32_e32 v97, v66
	v_mov_b32_e32 v2, v66
	v_mov_b32_e32 v3, v66
	v_mov_b32_e32 v4, v66
	v_mov_b32_e32 v5, v66
	v_mov_b32_e32 v6, v66
	v_mov_b32_e32 v7, v66
	v_mov_b32_e32 v8, v66
	v_mov_b32_e32 v9, v66
	v_mov_b32_e32 v10, v66
	v_mov_b32_e32 v11, v66
	v_mov_b32_e32 v12, v66
	v_mov_b32_e32 v13, v66
	v_mov_b32_e32 v14, v66
	v_mov_b32_e32 v15, v66
	v_mov_b32_e32 v16, v66
	v_mov_b32_e32 v17, v66
	v_mov_b32_e32 v18, v66
	v_mov_b32_e32 v19, v66
	v_mov_b32_e32 v20, v66
	v_mov_b32_e32 v21, v66
	v_mov_b32_e32 v22, v66
	v_mov_b32_e32 v23, v66
	v_mov_b32_e32 v24, v66
	v_mov_b32_e32 v25, v66
	v_mov_b32_e32 v26, v66
	v_mov_b32_e32 v27, v66
	v_mov_b32_e32 v28, v66
	v_mov_b32_e32 v29, v66
	v_mov_b32_e32 v30, v66
	v_mov_b32_e32 v31, v66
	v_mov_b32_e32 v32, v66
	v_mov_b32_e32 v33, v66
	v_mov_b32_e32 v98, v66
	v_mov_b32_e32 v99, v66
	v_mov_b32_e32 v100, v66
	v_mov_b32_e32 v101, v66
	v_mov_b32_e32 v102, v66
	v_mov_b32_e32 v103, v66
	v_mov_b32_e32 v104, v66
	v_mov_b32_e32 v105, v66
	v_mov_b32_e32 v106, v66
	v_mov_b32_e32 v107, v66
	v_mov_b32_e32 v108, v66
	v_mov_b32_e32 v109, v66
	v_mov_b32_e32 v110, v66
	v_mov_b32_e32 v111, v66
	v_mov_b32_e32 v112, v66
	v_mov_b32_e32 v113, v66
	v_mov_b32_e32 v114, v66
	v_mov_b32_e32 v115, v66
	v_mov_b32_e32 v116, v66
	v_mov_b32_e32 v117, v66
	v_mov_b32_e32 v118, v66
	v_mov_b32_e32 v119, v66
	v_mov_b32_e32 v120, v66
	v_mov_b32_e32 v121, v66
	v_mov_b32_e32 v122, v66
	v_mov_b32_e32 v123, v66
	v_mov_b32_e32 v124, v66
	v_mov_b32_e32 v125, v66
	v_mov_b32_e32 v126, v66
	v_mov_b32_e32 v127, v66
	v_mov_b32_e32 v128, v66
	v_mov_b32_e32 v129, v66
	v_mov_b32_e32 v34, v66
	v_mov_b32_e32 v35, v66
	v_mov_b32_e32 v36, v66
	v_mov_b32_e32 v37, v66
	v_mov_b32_e32 v38, v66
	v_mov_b32_e32 v39, v66
	v_mov_b32_e32 v40, v66
	v_mov_b32_e32 v41, v66
	v_mov_b32_e32 v42, v66
	v_mov_b32_e32 v43, v66
	v_mov_b32_e32 v44, v66
	v_mov_b32_e32 v45, v66
	v_mov_b32_e32 v46, v66
	v_mov_b32_e32 v47, v66
	v_mov_b32_e32 v48, v66
	v_mov_b32_e32 v49, v66
	v_mov_b32_e32 v50, v66
	v_mov_b32_e32 v51, v66
	v_mov_b32_e32 v52, v66
	v_mov_b32_e32 v53, v66
	v_mov_b32_e32 v54, v66
	v_mov_b32_e32 v55, v66
	v_mov_b32_e32 v56, v66
	v_mov_b32_e32 v57, v66
	v_mov_b32_e32 v58, v66
	v_mov_b32_e32 v59, v66
	v_mov_b32_e32 v60, v66
	v_mov_b32_e32 v61, v66
	v_mov_b32_e32 v62, v66
	v_mov_b32_e32 v63, v66
	v_mov_b32_e32 v64, v66
	v_mov_b32_e32 v65, v66
	s_waitcnt vmcnt(0)

.LBB0_535:
	s_ashr_i32 s21, s20, 31
	s_lshl_b64 s[22:23], s[20:21], 21
	v_readlane_b32 s24, v251, 17
	v_readlane_b32 s25, v251, 18
	s_add_u32 s22, s24, s22
	s_addc_u32 s23, s25, s23
	s_and_b64 s[24:25], s[2:3], exec
	s_cselect_b32 s21, s23, s27
	s_cselect_b32 s74, s22, s26
	s_ashr_i32 s19, s18, 31
	s_lshl_b64 s[24:25], s[18:19], 21
	s_add_u32 s24, s39, s24
	s_addc_u32 s25, s40, s25
	s_and_b64 s[34:35], s[2:3], exec
	s_cselect_b32 s19, s25, s31
	s_cselect_b32 s75, s24, s30
	s_add_u32 s26, s26, 0x104000
	s_addc_u32 s27, s27, 0
	s_add_u32 s78, s30, 0x8000
	v_mov_b32_e32 v66, 0
	s_addc_u32 s79, s31, 0
	s_mov_b32 s80, -2
	v_mov_b32_e32 v67, v66
	v_mov_b32_e32 v68, v66
	v_mov_b32_e32 v69, v66
	v_mov_b32_e32 v70, v66
	v_mov_b32_e32 v71, v66
	v_mov_b32_e32 v72, v66
	v_mov_b32_e32 v73, v66
	v_mov_b32_e32 v74, v66
	v_mov_b32_e32 v75, v66
	v_mov_b32_e32 v76, v66
	v_mov_b32_e32 v77, v66
	v_mov_b32_e32 v78, v66
	v_mov_b32_e32 v79, v66
	v_mov_b32_e32 v80, v66
	v_mov_b32_e32 v81, v66
	v_mov_b32_e32 v82, v66
	v_mov_b32_e32 v83, v66
	v_mov_b32_e32 v84, v66
	v_mov_b32_e32 v85, v66
	v_mov_b32_e32 v86, v66
	v_mov_b32_e32 v87, v66
	v_mov_b32_e32 v88, v66
	v_mov_b32_e32 v89, v66
	v_mov_b32_e32 v90, v66
	v_mov_b32_e32 v91, v66
	v_mov_b32_e32 v92, v66
	v_mov_b32_e32 v93, v66
	v_mov_b32_e32 v94, v66
	v_mov_b32_e32 v95, v66
	v_mov_b32_e32 v96, v66
	v_mov_b32_e32 v97, v66
	v_mov_b32_e32 v2, v66
	v_mov_b32_e32 v3, v66
	v_mov_b32_e32 v4, v66
	v_mov_b32_e32 v5, v66
	v_mov_b32_e32 v6, v66
	v_mov_b32_e32 v7, v66
	v_mov_b32_e32 v8, v66
	v_mov_b32_e32 v9, v66
	v_mov_b32_e32 v10, v66
	v_mov_b32_e32 v11, v66
	v_mov_b32_e32 v12, v66
	v_mov_b32_e32 v13, v66
	v_mov_b32_e32 v14, v66
	v_mov_b32_e32 v15, v66
	v_mov_b32_e32 v16, v66
	v_mov_b32_e32 v17, v66
	v_mov_b32_e32 v18, v66
	v_mov_b32_e32 v19, v66
	v_mov_b32_e32 v20, v66
	v_mov_b32_e32 v21, v66
	v_mov_b32_e32 v22, v66
	v_mov_b32_e32 v23, v66
	v_mov_b32_e32 v24, v66
	v_mov_b32_e32 v25, v66
	v_mov_b32_e32 v26, v66
	v_mov_b32_e32 v27, v66
	v_mov_b32_e32 v28, v66
	v_mov_b32_e32 v29, v66
	v_mov_b32_e32 v30, v66
	v_mov_b32_e32 v31, v66
	v_mov_b32_e32 v32, v66
	v_mov_b32_e32 v33, v66
	v_mov_b32_e32 v98, v66
	v_mov_b32_e32 v99, v66
	v_mov_b32_e32 v100, v66
	v_mov_b32_e32 v101, v66
	v_mov_b32_e32 v102, v66
	v_mov_b32_e32 v103, v66
	v_mov_b32_e32 v104, v66
	v_mov_b32_e32 v105, v66
	v_mov_b32_e32 v106, v66
	v_mov_b32_e32 v107, v66
	v_mov_b32_e32 v108, v66
	v_mov_b32_e32 v109, v66
	v_mov_b32_e32 v110, v66
	v_mov_b32_e32 v111, v66
	v_mov_b32_e32 v112, v66
	v_mov_b32_e32 v113, v66
	v_mov_b32_e32 v114, v66
	v_mov_b32_e32 v115, v66
	v_mov_b32_e32 v116, v66
	v_mov_b32_e32 v117, v66
	v_mov_b32_e32 v118, v66
	v_mov_b32_e32 v119, v66
	v_mov_b32_e32 v120, v66
	v_mov_b32_e32 v121, v66
	v_mov_b32_e32 v122, v66
	v_mov_b32_e32 v123, v66
	v_mov_b32_e32 v124, v66
	v_mov_b32_e32 v125, v66
	v_mov_b32_e32 v126, v66
	v_mov_b32_e32 v127, v66
	v_mov_b32_e32 v128, v66
	v_mov_b32_e32 v129, v66
	v_mov_b32_e32 v34, v66
	v_mov_b32_e32 v35, v66
	v_mov_b32_e32 v36, v66
	v_mov_b32_e32 v37, v66
	v_mov_b32_e32 v38, v66
	v_mov_b32_e32 v39, v66
	v_mov_b32_e32 v40, v66
	v_mov_b32_e32 v41, v66
	v_mov_b32_e32 v42, v66
	v_mov_b32_e32 v43, v66
	v_mov_b32_e32 v44, v66
	v_mov_b32_e32 v45, v66
	v_mov_b32_e32 v46, v66
	v_mov_b32_e32 v47, v66
	v_mov_b32_e32 v48, v66
	v_mov_b32_e32 v49, v66
	v_mov_b32_e32 v50, v66
	v_mov_b32_e32 v51, v66
	v_mov_b32_e32 v52, v66
	v_mov_b32_e32 v53, v66
	v_mov_b32_e32 v54, v66
	v_mov_b32_e32 v55, v66
	v_mov_b32_e32 v56, v66
	v_mov_b32_e32 v57, v66
	v_mov_b32_e32 v58, v66
	v_mov_b32_e32 v59, v66
	v_mov_b32_e32 v60, v66
	v_mov_b32_e32 v61, v66
	v_mov_b32_e32 v62, v66
	v_mov_b32_e32 v63, v66
	v_mov_b32_e32 v64, v66
	v_mov_b32_e32 v65, v66
	s_waitcnt vmcnt(0)

.LBB0_1004:
	s_cmp_lg_u32 s30, 0
	s_cselect_b64 s[22:23], -1, 0
	s_cmp_eq_u32 s30, 0
	s_cselect_b32 s66, 32, 16
	s_add_i32 s67, s66, -2
	s_add_u32 s24, s24, 0xc4000
	s_addc_u32 s25, s25, 0
	s_add_u32 s68, s26, 0x8000
	s_mov_b32 s31, 0
	s_addc_u32 s69, s27, 0
	s_waitcnt vmcnt(0)

.LBB0_1087:
	s_ashr_i32 s25, s24, 31
	s_lshl_b64 s[26:27], s[24:25], 21
	s_add_u32 s26, s28, s26
	s_addc_u32 s27, s29, s27
	s_and_b64 s[30:31], s[6:7], exec
	s_cselect_b32 s25, s27, s37
	s_cselect_b32 s35, s26, s36
	s_ashr_i32 s23, s22, 31
	s_lshl_b64 s[30:31], s[22:23], 21
	s_add_u32 s30, s52, s30
	s_addc_u32 s31, s53, s31
	s_and_b64 s[40:41], s[6:7], exec
	s_cselect_b32 s23, s31, s39
	s_cselect_b32 s69, s30, s38
	s_add_u32 s36, s36, 0x104000
	s_addc_u32 s37, s37, 0
	s_add_u32 s70, s38, 0x8000
	v_mov_b32_e32 v2, 0
	s_addc_u32 s71, s39, 0
	s_mov_b32 s72, -2
	s_waitcnt lgkmcnt(0)
	v_mov_b32_e32 v3, v2
	v_mov_b32_e32 v4, v2
	v_mov_b32_e32 v5, v2
	v_mov_b32_e32 v6, v2
	v_mov_b32_e32 v7, v2
	v_mov_b32_e32 v8, v2
	v_mov_b32_e32 v9, v2
	v_mov_b32_e32 v18, v2
	v_mov_b32_e32 v19, v2
	v_mov_b32_e32 v20, v2
	v_mov_b32_e32 v21, v2
	v_mov_b32_e32 v22, v2
	v_mov_b32_e32 v23, v2
	v_mov_b32_e32 v24, v2
	v_mov_b32_e32 v25, v2
	v_mov_b32_e32 v34, v2
	v_mov_b32_e32 v35, v2
	v_mov_b32_e32 v36, v2
	v_mov_b32_e32 v37, v2
	v_mov_b32_e32 v38, v2
	v_mov_b32_e32 v39, v2
	v_mov_b32_e32 v40, v2
	v_mov_b32_e32 v41, v2
	v_mov_b32_e32 v50, v2
	v_mov_b32_e32 v51, v2
	v_mov_b32_e32 v52, v2
	v_mov_b32_e32 v53, v2
	v_mov_b32_e32 v54, v2
	v_mov_b32_e32 v55, v2
	v_mov_b32_e32 v56, v2
	v_mov_b32_e32 v57, v2
	v_mov_b32_e32 v10, v2
	v_mov_b32_e32 v11, v2
	v_mov_b32_e32 v12, v2
	v_mov_b32_e32 v13, v2
	v_mov_b32_e32 v14, v2
	v_mov_b32_e32 v15, v2
	v_mov_b32_e32 v16, v2
	v_mov_b32_e32 v17, v2
	v_mov_b32_e32 v26, v2
	v_mov_b32_e32 v27, v2
	v_mov_b32_e32 v28, v2
	v_mov_b32_e32 v29, v2
	v_mov_b32_e32 v30, v2
	v_mov_b32_e32 v31, v2
	v_mov_b32_e32 v32, v2
	v_mov_b32_e32 v33, v2
	v_mov_b32_e32 v42, v2
	v_mov_b32_e32 v43, v2
	v_mov_b32_e32 v44, v2
	v_mov_b32_e32 v45, v2
	v_mov_b32_e32 v46, v2
	v_mov_b32_e32 v47, v2
	v_mov_b32_e32 v48, v2
	v_mov_b32_e32 v49, v2
	v_mov_b32_e32 v58, v2
	v_mov_b32_e32 v59, v2
	v_mov_b32_e32 v60, v2
	v_mov_b32_e32 v61, v2
	v_mov_b32_e32 v62, v2
	v_mov_b32_e32 v63, v2
	v_mov_b32_e32 v64, v2
	v_mov_b32_e32 v65, v2
	v_mov_b32_e32 v66, v2
	v_mov_b32_e32 v67, v2
	v_mov_b32_e32 v68, v2
	v_mov_b32_e32 v69, v2
	v_mov_b32_e32 v70, v2
	v_mov_b32_e32 v71, v2
	v_mov_b32_e32 v72, v2
	v_mov_b32_e32 v73, v2
	v_mov_b32_e32 v82, v2
	v_mov_b32_e32 v83, v2
	v_mov_b32_e32 v84, v2
	v_mov_b32_e32 v85, v2
	v_mov_b32_e32 v86, v2
	v_mov_b32_e32 v87, v2
	v_mov_b32_e32 v88, v2
	v_mov_b32_e32 v89, v2
	v_mov_b32_e32 v98, v2
	v_mov_b32_e32 v99, v2
	v_mov_b32_e32 v100, v2
	v_mov_b32_e32 v101, v2
	v_mov_b32_e32 v102, v2
	v_mov_b32_e32 v103, v2
	v_mov_b32_e32 v104, v2
	v_mov_b32_e32 v105, v2
	v_mov_b32_e32 v114, v2
	v_mov_b32_e32 v115, v2
	v_mov_b32_e32 v116, v2
	v_mov_b32_e32 v117, v2
	v_mov_b32_e32 v118, v2
	v_mov_b32_e32 v119, v2
	v_mov_b32_e32 v120, v2
	v_mov_b32_e32 v121, v2
	v_mov_b32_e32 v74, v2
	v_mov_b32_e32 v75, v2
	v_mov_b32_e32 v76, v2
	v_mov_b32_e32 v77, v2
	v_mov_b32_e32 v78, v2
	v_mov_b32_e32 v79, v2
	v_mov_b32_e32 v80, v2
	v_mov_b32_e32 v81, v2
	v_mov_b32_e32 v90, v2
	v_mov_b32_e32 v91, v2
	v_mov_b32_e32 v92, v2
	v_mov_b32_e32 v93, v2
	v_mov_b32_e32 v94, v2
	v_mov_b32_e32 v95, v2
	v_mov_b32_e32 v96, v2
	v_mov_b32_e32 v97, v2
	v_mov_b32_e32 v106, v2
	v_mov_b32_e32 v107, v2
	v_mov_b32_e32 v108, v2
	v_mov_b32_e32 v109, v2
	v_mov_b32_e32 v110, v2
	v_mov_b32_e32 v111, v2
	v_mov_b32_e32 v112, v2
	v_mov_b32_e32 v113, v2
	v_mov_b32_e32 v122, v2
	v_mov_b32_e32 v123, v2
	v_mov_b32_e32 v124, v2
	v_mov_b32_e32 v125, v2
	v_mov_b32_e32 v126, v2
	v_mov_b32_e32 v127, v2
	v_mov_b32_e32 v128, v2
	v_mov_b32_e32 v129, v2
	s_waitcnt vmcnt(0)

.LBB0_1214:
	s_ashr_i32 s21, s20, 31
	s_lshl_b64 s[22:23], s[20:21], 21
	s_add_u32 s22, s10, s22
	s_addc_u32 s23, s11, s23
	s_and_b64 s[24:25], s[4:5], exec
	s_cselect_b32 s21, s23, s29
	s_cselect_b32 s56, s22, s28
	s_ashr_i32 s19, s18, 31
	s_lshl_b64 s[24:25], s[18:19], 21
	s_add_u32 s24, s65, s24
	v_readlane_b32 s19, v251, 50
	s_addc_u32 s25, s19, s25
	s_and_b64 s[34:35], s[4:5], exec
	s_cselect_b32 s19, s25, s31
	s_cselect_b32 s57, s24, s30
	s_add_u32 s28, s28, 0x104000
	s_addc_u32 s29, s29, 0
	s_add_u32 s59, s30, 0x8000
	v_mov_b32_e32 v2, 0
	s_addc_u32 s60, s31, 0
	s_mov_b32 s61, -2
	v_mov_b32_e32 v3, v2
	v_mov_b32_e32 v4, v2
	v_mov_b32_e32 v5, v2
	v_mov_b32_e32 v6, v2
	v_mov_b32_e32 v7, v2
	v_mov_b32_e32 v8, v2
	v_mov_b32_e32 v9, v2
	v_mov_b32_e32 v18, v2
	v_mov_b32_e32 v19, v2
	v_mov_b32_e32 v20, v2
	v_mov_b32_e32 v21, v2
	v_mov_b32_e32 v22, v2
	v_mov_b32_e32 v23, v2
	v_mov_b32_e32 v24, v2
	v_mov_b32_e32 v25, v2
	v_mov_b32_e32 v34, v2
	v_mov_b32_e32 v35, v2
	v_mov_b32_e32 v36, v2
	v_mov_b32_e32 v37, v2
	v_mov_b32_e32 v38, v2
	v_mov_b32_e32 v39, v2
	v_mov_b32_e32 v40, v2
	v_mov_b32_e32 v41, v2
	v_mov_b32_e32 v50, v2
	v_mov_b32_e32 v51, v2
	v_mov_b32_e32 v52, v2
	v_mov_b32_e32 v53, v2
	v_mov_b32_e32 v54, v2
	v_mov_b32_e32 v55, v2
	v_mov_b32_e32 v56, v2
	v_mov_b32_e32 v57, v2
	v_mov_b32_e32 v10, v2
	v_mov_b32_e32 v11, v2
	v_mov_b32_e32 v12, v2
	v_mov_b32_e32 v13, v2
	v_mov_b32_e32 v14, v2
	v_mov_b32_e32 v15, v2
	v_mov_b32_e32 v16, v2
	v_mov_b32_e32 v17, v2
	v_mov_b32_e32 v26, v2
	v_mov_b32_e32 v27, v2
	v_mov_b32_e32 v28, v2
	v_mov_b32_e32 v29, v2
	v_mov_b32_e32 v30, v2
	v_mov_b32_e32 v31, v2
	v_mov_b32_e32 v32, v2
	v_mov_b32_e32 v33, v2
	v_mov_b32_e32 v42, v2
	v_mov_b32_e32 v43, v2
	v_mov_b32_e32 v44, v2
	v_mov_b32_e32 v45, v2
	v_mov_b32_e32 v46, v2
	v_mov_b32_e32 v47, v2
	v_mov_b32_e32 v48, v2
	v_mov_b32_e32 v49, v2
	v_mov_b32_e32 v58, v2
	v_mov_b32_e32 v59, v2
	v_mov_b32_e32 v60, v2
	v_mov_b32_e32 v61, v2
	v_mov_b32_e32 v62, v2
	v_mov_b32_e32 v63, v2
	v_mov_b32_e32 v64, v2
	v_mov_b32_e32 v65, v2
	v_mov_b32_e32 v66, v2
	v_mov_b32_e32 v67, v2
	v_mov_b32_e32 v68, v2
	v_mov_b32_e32 v69, v2
	v_mov_b32_e32 v70, v2
	v_mov_b32_e32 v71, v2
	v_mov_b32_e32 v72, v2
	v_mov_b32_e32 v73, v2
	v_mov_b32_e32 v82, v2
	v_mov_b32_e32 v83, v2
	v_mov_b32_e32 v84, v2
	v_mov_b32_e32 v85, v2
	v_mov_b32_e32 v86, v2
	v_mov_b32_e32 v87, v2
	v_mov_b32_e32 v88, v2
	v_mov_b32_e32 v89, v2
	v_mov_b32_e32 v98, v2
	v_mov_b32_e32 v99, v2
	v_mov_b32_e32 v100, v2
	v_mov_b32_e32 v101, v2
	v_mov_b32_e32 v102, v2
	v_mov_b32_e32 v103, v2
	v_mov_b32_e32 v104, v2
	v_mov_b32_e32 v105, v2
	v_mov_b32_e32 v114, v2
	v_mov_b32_e32 v115, v2
	v_mov_b32_e32 v116, v2
	v_mov_b32_e32 v117, v2
	v_mov_b32_e32 v118, v2
	v_mov_b32_e32 v119, v2
	v_mov_b32_e32 v120, v2
	v_mov_b32_e32 v121, v2
	v_mov_b32_e32 v74, v2
	v_mov_b32_e32 v75, v2
	v_mov_b32_e32 v76, v2
	v_mov_b32_e32 v77, v2
	v_mov_b32_e32 v78, v2
	v_mov_b32_e32 v79, v2
	v_mov_b32_e32 v80, v2
	v_mov_b32_e32 v81, v2
	v_mov_b32_e32 v90, v2
	v_mov_b32_e32 v91, v2
	v_mov_b32_e32 v92, v2
	v_mov_b32_e32 v93, v2
	v_mov_b32_e32 v94, v2
	v_mov_b32_e32 v95, v2
	v_mov_b32_e32 v96, v2
	v_mov_b32_e32 v97, v2
	v_mov_b32_e32 v106, v2
	v_mov_b32_e32 v107, v2
	v_mov_b32_e32 v108, v2
	v_mov_b32_e32 v109, v2
	v_mov_b32_e32 v110, v2
	v_mov_b32_e32 v111, v2
	v_mov_b32_e32 v112, v2
	v_mov_b32_e32 v113, v2
	v_mov_b32_e32 v122, v2
	v_mov_b32_e32 v123, v2
	v_mov_b32_e32 v124, v2
	v_mov_b32_e32 v125, v2
	v_mov_b32_e32 v126, v2
	v_mov_b32_e32 v127, v2
	v_mov_b32_e32 v128, v2
	v_mov_b32_e32 v129, v2
	s_waitcnt vmcnt(0)

.LBB0_1291:
	s_ashr_i32 s29, s28, 31
	s_lshl_b64 s[30:31], s[28:29], 23
	s_add_u32 s30, s84, s30
	s_addc_u32 s31, s85, s31
	s_and_b64 s[34:35], s[6:7], exec
	s_cselect_b32 s14, s31, s41
	s_cselect_b32 s29, s30, s40
	s_ashr_i32 s27, s26, 31
	s_lshl_b64 s[34:35], s[26:27], 23
	s_add_u32 s34, s51, s34
	v_readlane_b32 s27, v251, 62
	s_addc_u32 s35, s27, s35
	s_and_b64 s[44:45], s[6:7], exec
	s_cselect_b32 s27, s35, s43
	s_cselect_b32 s37, s34, s42
	s_add_u32 s40, s40, 0x404000
	s_addc_u32 s41, s41, 0
	s_add_u32 s39, s42, 0x8000
	v_mov_b32_e32 v2, 0
	s_addc_u32 s65, s43, 0
	s_mov_b32 s66, -2
	s_waitcnt lgkmcnt(0)
	v_mov_b32_e32 v3, v2
	v_mov_b32_e32 v4, v2
	v_mov_b32_e32 v5, v2
	v_mov_b32_e32 v6, v2
	v_mov_b32_e32 v7, v2
	v_mov_b32_e32 v8, v2
	v_mov_b32_e32 v9, v2
	v_mov_b32_e32 v18, v2
	v_mov_b32_e32 v19, v2
	v_mov_b32_e32 v20, v2
	v_mov_b32_e32 v21, v2
	v_mov_b32_e32 v22, v2
	v_mov_b32_e32 v23, v2
	v_mov_b32_e32 v24, v2
	v_mov_b32_e32 v25, v2
	v_mov_b32_e32 v34, v2
	v_mov_b32_e32 v35, v2
	v_mov_b32_e32 v36, v2
	v_mov_b32_e32 v37, v2
	v_mov_b32_e32 v38, v2
	v_mov_b32_e32 v39, v2
	v_mov_b32_e32 v40, v2
	v_mov_b32_e32 v41, v2
	v_mov_b32_e32 v50, v2
	v_mov_b32_e32 v51, v2
	v_mov_b32_e32 v52, v2
	v_mov_b32_e32 v53, v2
	v_mov_b32_e32 v54, v2
	v_mov_b32_e32 v55, v2
	v_mov_b32_e32 v56, v2
	v_mov_b32_e32 v57, v2
	v_mov_b32_e32 v10, v2
	v_mov_b32_e32 v11, v2
	v_mov_b32_e32 v12, v2
	v_mov_b32_e32 v13, v2
	v_mov_b32_e32 v14, v2
	v_mov_b32_e32 v15, v2
	v_mov_b32_e32 v16, v2
	v_mov_b32_e32 v17, v2
	v_mov_b32_e32 v26, v2
	v_mov_b32_e32 v27, v2
	v_mov_b32_e32 v28, v2
	v_mov_b32_e32 v29, v2
	v_mov_b32_e32 v30, v2
	v_mov_b32_e32 v31, v2
	v_mov_b32_e32 v32, v2
	v_mov_b32_e32 v33, v2
	v_mov_b32_e32 v42, v2
	v_mov_b32_e32 v43, v2
	v_mov_b32_e32 v44, v2
	v_mov_b32_e32 v45, v2
	v_mov_b32_e32 v46, v2
	v_mov_b32_e32 v47, v2
	v_mov_b32_e32 v48, v2
	v_mov_b32_e32 v49, v2
	v_mov_b32_e32 v58, v2
	v_mov_b32_e32 v59, v2
	v_mov_b32_e32 v60, v2
	v_mov_b32_e32 v61, v2
	v_mov_b32_e32 v62, v2
	v_mov_b32_e32 v63, v2
	v_mov_b32_e32 v64, v2
	v_mov_b32_e32 v65, v2
	v_mov_b32_e32 v66, v2
	v_mov_b32_e32 v67, v2
	v_mov_b32_e32 v68, v2
	v_mov_b32_e32 v69, v2
	v_mov_b32_e32 v70, v2
	v_mov_b32_e32 v71, v2
	v_mov_b32_e32 v72, v2
	v_mov_b32_e32 v73, v2
	v_mov_b32_e32 v82, v2
	v_mov_b32_e32 v83, v2
	v_mov_b32_e32 v84, v2
	v_mov_b32_e32 v85, v2
	v_mov_b32_e32 v86, v2
	v_mov_b32_e32 v87, v2
	v_mov_b32_e32 v88, v2
	v_mov_b32_e32 v89, v2
	v_mov_b32_e32 v98, v2
	v_mov_b32_e32 v99, v2
	v_mov_b32_e32 v100, v2
	v_mov_b32_e32 v101, v2
	v_mov_b32_e32 v102, v2
	v_mov_b32_e32 v103, v2
	v_mov_b32_e32 v104, v2
	v_mov_b32_e32 v105, v2
	v_mov_b32_e32 v114, v2
	v_mov_b32_e32 v115, v2
	v_mov_b32_e32 v116, v2
	v_mov_b32_e32 v117, v2
	v_mov_b32_e32 v118, v2
	v_mov_b32_e32 v119, v2
	v_mov_b32_e32 v120, v2
	v_mov_b32_e32 v121, v2
	v_mov_b32_e32 v74, v2
	v_mov_b32_e32 v75, v2
	v_mov_b32_e32 v76, v2
	v_mov_b32_e32 v77, v2
	v_mov_b32_e32 v78, v2
	v_mov_b32_e32 v79, v2
	v_mov_b32_e32 v80, v2
	v_mov_b32_e32 v81, v2
	v_mov_b32_e32 v90, v2
	v_mov_b32_e32 v91, v2
	v_mov_b32_e32 v92, v2
	v_mov_b32_e32 v93, v2
	v_mov_b32_e32 v94, v2
	v_mov_b32_e32 v95, v2
	v_mov_b32_e32 v96, v2
	v_mov_b32_e32 v97, v2
	v_mov_b32_e32 v106, v2
	v_mov_b32_e32 v107, v2
	v_mov_b32_e32 v108, v2
	v_mov_b32_e32 v109, v2
	v_mov_b32_e32 v110, v2
	v_mov_b32_e32 v111, v2
	v_mov_b32_e32 v112, v2
	v_mov_b32_e32 v113, v2
	v_mov_b32_e32 v122, v2
	v_mov_b32_e32 v123, v2
	v_mov_b32_e32 v124, v2
	v_mov_b32_e32 v125, v2
	v_mov_b32_e32 v126, v2
	v_mov_b32_e32 v127, v2
	v_mov_b32_e32 v128, v2
	v_mov_b32_e32 v129, v2
	s_waitcnt vmcnt(0)

.LBB0_1386:
	s_ashr_i32 s21, s20, 31
	s_lshl_b64 s[22:23], s[20:21], 21
	s_add_u32 s22, s0, s22
	s_addc_u32 s23, s1, s23
	s_and_b64 s[24:25], s[2:3], exec
	s_cselect_b32 s21, s23, s31
	s_cselect_b32 s27, s22, s30
	s_ashr_i32 s19, s18, 31
	s_lshl_b64 s[24:25], s[18:19], 21
	s_add_u32 s24, s48, s24
	s_addc_u32 s25, s49, s25
	s_and_b64 s[36:37], s[2:3], exec
	s_cselect_b32 s19, s25, s35
	s_cselect_b32 s29, s24, s34
	s_add_u32 s30, s30, 0x104000
	s_addc_u32 s31, s31, 0
	s_add_u32 s52, s34, 0x8000
	v_mov_b32_e32 v2, 0
	s_addc_u32 s53, s35, 0
	s_mov_b32 s54, -2
	v_mov_b32_e32 v3, v2
	v_mov_b32_e32 v4, v2
	v_mov_b32_e32 v5, v2
	v_mov_b32_e32 v6, v2
	v_mov_b32_e32 v7, v2
	v_mov_b32_e32 v8, v2
	v_mov_b32_e32 v9, v2
	v_mov_b32_e32 v18, v2
	v_mov_b32_e32 v19, v2
	v_mov_b32_e32 v20, v2
	v_mov_b32_e32 v21, v2
	v_mov_b32_e32 v22, v2
	v_mov_b32_e32 v23, v2
	v_mov_b32_e32 v24, v2
	v_mov_b32_e32 v25, v2
	v_mov_b32_e32 v34, v2
	v_mov_b32_e32 v35, v2
	v_mov_b32_e32 v36, v2
	v_mov_b32_e32 v37, v2
	v_mov_b32_e32 v38, v2
	v_mov_b32_e32 v39, v2
	v_mov_b32_e32 v40, v2
	v_mov_b32_e32 v41, v2
	v_mov_b32_e32 v50, v2
	v_mov_b32_e32 v51, v2
	v_mov_b32_e32 v52, v2
	v_mov_b32_e32 v53, v2
	v_mov_b32_e32 v54, v2
	v_mov_b32_e32 v55, v2
	v_mov_b32_e32 v56, v2
	v_mov_b32_e32 v57, v2
	v_mov_b32_e32 v10, v2
	v_mov_b32_e32 v11, v2
	v_mov_b32_e32 v12, v2
	v_mov_b32_e32 v13, v2
	v_mov_b32_e32 v14, v2
	v_mov_b32_e32 v15, v2
	v_mov_b32_e32 v16, v2
	v_mov_b32_e32 v17, v2
	v_mov_b32_e32 v26, v2
	v_mov_b32_e32 v27, v2
	v_mov_b32_e32 v28, v2
	v_mov_b32_e32 v29, v2
	v_mov_b32_e32 v30, v2
	v_mov_b32_e32 v31, v2
	v_mov_b32_e32 v32, v2
	v_mov_b32_e32 v33, v2
	v_mov_b32_e32 v42, v2
	v_mov_b32_e32 v43, v2
	v_mov_b32_e32 v44, v2
	v_mov_b32_e32 v45, v2
	v_mov_b32_e32 v46, v2
	v_mov_b32_e32 v47, v2
	v_mov_b32_e32 v48, v2
	v_mov_b32_e32 v49, v2
	v_mov_b32_e32 v58, v2
	v_mov_b32_e32 v59, v2
	v_mov_b32_e32 v60, v2
	v_mov_b32_e32 v61, v2
	v_mov_b32_e32 v70, v2
	v_mov_b32_e32 v71, v2
	v_mov_b32_e32 v72, v2
	v_mov_b32_e32 v73, v2
	v_mov_b32_e32 v82, v2
	v_mov_b32_e32 v83, v2
	v_mov_b32_e32 v84, v2
	v_mov_b32_e32 v85, v2
	v_mov_b32_e32 v86, v2
	v_mov_b32_e32 v87, v2
	v_mov_b32_e32 v88, v2
	v_mov_b32_e32 v89, v2
	v_mov_b32_e32 v98, v2
	v_mov_b32_e32 v99, v2
	v_mov_b32_e32 v100, v2
	v_mov_b32_e32 v101, v2
	v_mov_b32_e32 v102, v2
	v_mov_b32_e32 v103, v2
	v_mov_b32_e32 v104, v2
	v_mov_b32_e32 v105, v2
	v_mov_b32_e32 v114, v2
	v_mov_b32_e32 v115, v2
	v_mov_b32_e32 v116, v2
	v_mov_b32_e32 v117, v2
	v_mov_b32_e32 v118, v2
	v_mov_b32_e32 v119, v2
	v_mov_b32_e32 v120, v2
	v_mov_b32_e32 v121, v2
	v_mov_b32_e32 v130, v2
	v_mov_b32_e32 v131, v2
	v_mov_b32_e32 v132, v2
	v_mov_b32_e32 v133, v2
	v_mov_b32_e32 v134, v2
	v_mov_b32_e32 v135, v2
	v_mov_b32_e32 v136, v2
	v_mov_b32_e32 v137, v2
	v_mov_b32_e32 v90, v2
	v_mov_b32_e32 v91, v2
	v_mov_b32_e32 v92, v2
	v_mov_b32_e32 v93, v2
	v_mov_b32_e32 v94, v2
	v_mov_b32_e32 v95, v2
	v_mov_b32_e32 v96, v2
	v_mov_b32_e32 v97, v2
	v_mov_b32_e32 v106, v2
	v_mov_b32_e32 v107, v2
	v_mov_b32_e32 v108, v2
	v_mov_b32_e32 v109, v2
	v_mov_b32_e32 v110, v2
	v_mov_b32_e32 v111, v2
	v_mov_b32_e32 v112, v2
	v_mov_b32_e32 v113, v2
	v_mov_b32_e32 v122, v2
	v_mov_b32_e32 v123, v2
	v_mov_b32_e32 v124, v2
	v_mov_b32_e32 v125, v2
	v_mov_b32_e32 v126, v2
	v_mov_b32_e32 v127, v2
	v_mov_b32_e32 v128, v2
	v_mov_b32_e32 v129, v2
	v_mov_b32_e32 v138, v2
	v_mov_b32_e32 v139, v2
	v_mov_b32_e32 v140, v2
	v_mov_b32_e32 v141, v2
	v_mov_b32_e32 v142, v2
	v_mov_b32_e32 v143, v2
	v_mov_b32_e32 v144, v2
	v_mov_b32_e32 v145, v2
	s_waitcnt vmcnt(0)
